# in-proj GEMM K loop restructured: 4 segments of 32 MFMAs per 2 K-tiles (8 barriers instead of 16), LDS reads waited before barrier, vmcnt(8) DMA waits
# speedup vs baseline: 1.0098x; 1.0074x over previous
.LBB0_185:
	v_lshl_add_u64 v[8:9], s[70:71], 0, v[176:177]
	v_mov_b32_e32 v129, v177
	v_readlane_b32 s68, v254, 40
	s_lshl_b32 s2, s2, 5
	v_lshl_add_u64 v[10:11], s[70:71], 0, v[128:129]
	v_mov_b32_e32 v133, v177
	v_readlane_b32 s69, v254, 41
	s_and_b32 s13, s2, 0x60
	s_add_i32 m0, s60, 0x18000
	v_lshl_add_u64 v[8:9], v[8:9], 0, s[20:21]
	v_lshl_add_u64 v[12:13], s[68:69], 0, v[132:133]
	v_mov_b32_e32 v131, v177
	s_lshl_b32 s12, s1, 13
	s_lshl_b32 s14, s13, 7
	s_waitcnt vmcnt(2)
	s_barrier
	global_load_lds_dwordx4 v[8:9], off
	v_lshl_add_u64 v[8:9], v[10:11], 0, s[20:21]
	s_add_i32 m0, s60, 0x1a000
	s_add_i32 s76, s60, 0x8000
	s_add_i32 s77, s60, 0xa000
	v_lshl_add_u64 v[14:15], s[68:69], 0, v[130:131]
	global_load_lds_dwordx4 v[8:9], off
	v_lshl_add_u64 v[8:9], v[12:13], 0, s[20:21]
	s_mov_b32 m0, s76
	s_add_u32 s2, s70, 0x80080
	global_load_lds_dwordx4 v[8:9], off
	v_lshl_add_u64 v[8:9], v[14:15], 0, s[20:21]
	s_mov_b32 m0, s77
	s_addc_u32 s3, s71, 0
	global_load_lds_dwordx4 v[8:9], off
	s_add_i32 m0, s60, 0x1c000
	v_lshl_add_u64 v[8:9], s[2:3], 0, v[176:177]
	global_load_lds_dwordx4 v[8:9], off
	v_lshl_add_u64 v[8:9], s[2:3], 0, v[128:129]
	s_add_i32 m0, s60, 0x1e000
	v_and_b32_e32 v7, 15, v0
	global_load_lds_dwordx4 v[8:9], off
	v_lshrrev_b32_e32 v8, 1, v0
	v_and_b32_e32 v8, 24, v8
	v_lshlrev_b32_e32 v9, 1, v8
	v_lshlrev_b32_e32 v0, 2, v0
	v_lshl_or_b32 v142, s1, 6, v7
	v_lshl_or_b32 v7, v7, 6, v9
	v_and_b32_e32 v0, 32, v0
	v_bitop3_b32 v9, v7, s12, v0 bitop3:0xde
	v_bitop3_b32 v143, v7, s14, v0 bitop3:0xde
	v_lshlrev_b32_e32 v0, 15, v5
	v_and_b32_e32 v0, 0xffff0000, v0
	v_lshl_add_u32 v0, v4, 12, v0
	v_and_b32_e32 v4, 1, v5
	v_lshl_or_b32 v0, v4, 6, v0
	v_lshl_add_u32 v134, v6, 1, v0
	v_lshlrev_b32_e32 v0, 15, v1
	v_and_b32_e32 v0, 0xffff0000, v0
	s_waitcnt vmcnt(6)
	v_lshl_add_u32 v0, v2, 12, v0
	v_and_b32_e32 v1, 1, v1
	v_lshl_or_b32 v0, v1, 6, v0
	v_readlane_b32 s2, v254, 38
	v_or_b32_e32 v144, s13, v8
	v_mov_b32_e32 v135, v177
	v_lshl_add_u32 v136, v3, 1, v0
	v_mov_b32_e32 v137, v177
	s_mov_b32 s78, 0
	v_add_u32_e32 v145, 0, v9
	v_readlane_b32 s79, v254, 35
	s_mov_b32 s80, s2
	s_barrier
	v_readlane_b32 s3, v254, 39

.LBB0_189:
	s_add_u32 s1, s68, 0xfff80080
	s_addc_u32 s2, s69, -1
	v_add_u32_e32 v154, 0x10000, v143
	ds_read_b128 v[138:141], v154
	ds_read_b128 v[146:149], v154 offset:1024
	ds_read_b128 v[150:153], v154 offset:2048
	ds_read_b128 v[154:157], v154 offset:3072
	s_cmp_eq_u32 s87, 28
	s_cselect_b32 s73, s43, s2
	s_cselect_b32 s72, s81, s1
	s_cselect_b32 s71, s41, s86
	s_cselect_b32 s70, s82, s83
	v_add_u32_e32 v174, 0x14000, v143
	ds_read_b128 v[218:221], v174
	ds_read_b128 v[222:225], v174 offset:1024
	ds_read_b128 v[226:229], v174 offset:2048
	ds_read_b128 v[230:233], v174 offset:3072
	v_lshl_add_u64 v[234:235], s[68:69], 0, v[134:135]
	s_add_i32 m0, s60, 0xc000
	ds_read_b128 v[158:161], v145
	ds_read_b128 v[162:165], v145 offset:1024
	ds_read_b128 v[166:169], v145 offset:2048
	ds_read_b128 v[170:173], v145 offset:3072
	ds_read_b128 v[182:185], v145 offset:4096
	ds_read_b128 v[206:209], v145 offset:5120
	ds_read_b128 v[210:213], v145 offset:6144
	ds_read_b128 v[214:217], v145 offset:7168
	global_load_lds_dwordx4 v[234:235], off
	v_lshl_add_u64 v[234:235], s[68:69], 0, v[136:137]
	s_add_i32 m0, s60, 0xe000
	s_nop 0
	global_load_lds_dwordx4 v[234:235], off
	s_waitcnt lgkmcnt(0)
	s_waitcnt vmcnt(8)
	s_barrier
	s_setprio 1
	v_mfma_f32_16x16x32_bf16 v[124:127], v[138:141], v[158:161], v[124:127]
	v_mfma_f32_16x16x32_bf16 v[120:123], v[150:153], v[158:161], v[120:123]
	v_mfma_f32_16x16x32_bf16 v[116:119], v[138:141], v[166:169], v[116:119]
	v_mfma_f32_16x16x32_bf16 v[108:111], v[150:153], v[166:169], v[108:111]
	v_mfma_f32_16x16x32_bf16 v[100:103], v[138:141], v[182:185], v[100:103]
	v_mfma_f32_16x16x32_bf16 v[92:95], v[150:153], v[182:185], v[92:95]
	v_mfma_f32_16x16x32_bf16 v[84:87], v[138:141], v[210:213], v[84:87]
	v_mfma_f32_16x16x32_bf16 v[76:79], v[150:153], v[210:213], v[76:79]
	v_mfma_f32_16x16x32_bf16 v[124:127], v[146:149], v[162:165], v[124:127]
	v_mfma_f32_16x16x32_bf16 v[120:123], v[154:157], v[162:165], v[120:123]
	v_mfma_f32_16x16x32_bf16 v[116:119], v[146:149], v[170:173], v[116:119]
	v_mfma_f32_16x16x32_bf16 v[108:111], v[154:157], v[170:173], v[108:111]
	v_mfma_f32_16x16x32_bf16 v[100:103], v[146:149], v[206:209], v[100:103]
	v_mfma_f32_16x16x32_bf16 v[92:95], v[154:157], v[206:209], v[92:95]
	v_mfma_f32_16x16x32_bf16 v[84:87], v[146:149], v[214:217], v[84:87]
	v_mfma_f32_16x16x32_bf16 v[76:79], v[154:157], v[214:217], v[76:79]
	v_mfma_f32_16x16x32_bf16 v[112:115], v[218:221], v[158:161], v[112:115]
	v_mfma_f32_16x16x32_bf16 v[104:107], v[226:229], v[158:161], v[104:107]
	v_mfma_f32_16x16x32_bf16 v[96:99], v[218:221], v[166:169], v[96:99]
	v_mfma_f32_16x16x32_bf16 v[88:91], v[226:229], v[166:169], v[88:91]
	v_mfma_f32_16x16x32_bf16 v[80:83], v[218:221], v[182:185], v[80:83]
	v_mfma_f32_16x16x32_bf16 v[72:75], v[226:229], v[182:185], v[72:75]
	v_mfma_f32_16x16x32_bf16 v[68:71], v[218:221], v[210:213], v[68:71]
	v_mfma_f32_16x16x32_bf16 v[64:67], v[226:229], v[210:213], v[64:67]
	v_mfma_f32_16x16x32_bf16 v[112:115], v[222:225], v[162:165], v[112:115]
	v_mfma_f32_16x16x32_bf16 v[104:107], v[230:233], v[162:165], v[104:107]
	v_mfma_f32_16x16x32_bf16 v[96:99], v[222:225], v[170:173], v[96:99]
	v_mfma_f32_16x16x32_bf16 v[88:91], v[230:233], v[170:173], v[88:91]
	v_mfma_f32_16x16x32_bf16 v[80:83], v[222:225], v[206:209], v[80:83]
	v_mfma_f32_16x16x32_bf16 v[72:75], v[230:233], v[206:209], v[72:75]
	v_mfma_f32_16x16x32_bf16 v[68:71], v[222:225], v[214:217], v[68:71]
	v_mfma_f32_16x16x32_bf16 v[64:67], v[230:233], v[214:217], v[64:67]
	s_setprio 0
	s_barrier
	ds_read_b128 v[158:161], v145 offset:16384
	ds_read_b128 v[162:165], v145 offset:17408
	ds_read_b128 v[166:169], v145 offset:18432
	ds_read_b128 v[170:173], v145 offset:19456
	ds_read_b128 v[182:185], v145 offset:20480
	ds_read_b128 v[206:209], v145 offset:21504
	ds_read_b128 v[210:213], v145 offset:22528
	ds_read_b128 v[214:217], v145 offset:23552
	v_lshl_add_u64 v[174:175], s[70:71], 0, v[176:177]
	s_add_i32 m0, s53, 0x10000
	v_lshl_add_u64 v[186:187], s[70:71], 0, v[128:129]
	global_load_lds_dwordx4 v[174:175], off
	s_add_i32 m0, s53, 0x12000
	s_nop 0
	global_load_lds_dwordx4 v[186:187], off
	s_mov_b32 m0, s60
	v_lshl_add_u64 v[200:201], s[72:73], 0, v[132:133]
	v_lshl_add_u64 v[202:203], s[72:73], 0, v[130:131]
	global_load_lds_dwordx4 v[200:201], off
	s_mov_b32 m0, s61
	s_nop 0
	global_load_lds_dwordx4 v[202:203], off
	s_add_u32 s2, s70, 0x80000
	s_addc_u32 s3, s71, 0
	v_lshl_add_u64 v[234:235], s[2:3], 0, v[176:177]
	s_add_i32 m0, s53, 0x14000
	v_lshl_add_u64 v[236:237], s[2:3], 0, v[128:129]
	global_load_lds_dwordx4 v[234:235], off
	s_add_i32 m0, s53, 0x16000
	s_nop 0
	global_load_lds_dwordx4 v[236:237], off
	s_waitcnt lgkmcnt(0)
	s_waitcnt vmcnt(8)
	s_barrier
	s_setprio 1
	v_mfma_f32_16x16x32_bf16 v[60:63], v[138:141], v[158:161], v[60:63]
	v_mfma_f32_16x16x32_bf16 v[56:59], v[150:153], v[158:161], v[56:59]
	v_mfma_f32_16x16x32_bf16 v[52:55], v[138:141], v[166:169], v[52:55]
	v_mfma_f32_16x16x32_bf16 v[44:47], v[150:153], v[166:169], v[44:47]
	v_mfma_f32_16x16x32_bf16 v[36:39], v[138:141], v[182:185], v[36:39]
	v_mfma_f32_16x16x32_bf16 v[28:31], v[150:153], v[182:185], v[28:31]
	v_mfma_f32_16x16x32_bf16 v[20:23], v[138:141], v[210:213], v[20:23]
	v_mfma_f32_16x16x32_bf16 v[12:15], v[150:153], v[210:213], v[12:15]
	v_mfma_f32_16x16x32_bf16 v[60:63], v[146:149], v[162:165], v[60:63]
	v_mfma_f32_16x16x32_bf16 v[56:59], v[154:157], v[162:165], v[56:59]
	v_mfma_f32_16x16x32_bf16 v[52:55], v[146:149], v[170:173], v[52:55]
	v_mfma_f32_16x16x32_bf16 v[44:47], v[154:157], v[170:173], v[44:47]
	v_mfma_f32_16x16x32_bf16 v[36:39], v[146:149], v[206:209], v[36:39]
	v_mfma_f32_16x16x32_bf16 v[28:31], v[154:157], v[206:209], v[28:31]
	v_mfma_f32_16x16x32_bf16 v[20:23], v[146:149], v[214:217], v[20:23]
	v_mfma_f32_16x16x32_bf16 v[12:15], v[154:157], v[214:217], v[12:15]
	v_mfma_f32_16x16x32_bf16 v[48:51], v[218:221], v[158:161], v[48:51]
	v_mfma_f32_16x16x32_bf16 v[40:43], v[226:229], v[158:161], v[40:43]
	v_mfma_f32_16x16x32_bf16 v[32:35], v[218:221], v[166:169], v[32:35]
	v_mfma_f32_16x16x32_bf16 v[24:27], v[226:229], v[166:169], v[24:27]
	v_mfma_f32_16x16x32_bf16 v[16:19], v[218:221], v[182:185], v[16:19]
	v_mfma_f32_16x16x32_bf16 v[8:11], v[226:229], v[182:185], v[8:11]
	v_mfma_f32_16x16x32_bf16 v[4:7], v[218:221], v[210:213], v[4:7]
	v_mfma_f32_16x16x32_bf16 v[0:3], v[226:229], v[210:213], v[0:3]
	v_mfma_f32_16x16x32_bf16 v[48:51], v[222:225], v[162:165], v[48:51]
	v_mfma_f32_16x16x32_bf16 v[40:43], v[230:233], v[162:165], v[40:43]
	v_mfma_f32_16x16x32_bf16 v[32:35], v[222:225], v[170:173], v[32:35]
	v_mfma_f32_16x16x32_bf16 v[24:27], v[230:233], v[170:173], v[24:27]
	v_mfma_f32_16x16x32_bf16 v[16:19], v[222:225], v[206:209], v[16:19]
	v_mfma_f32_16x16x32_bf16 v[8:11], v[230:233], v[206:209], v[8:11]
	v_mfma_f32_16x16x32_bf16 v[4:7], v[222:225], v[214:217], v[4:7]
	v_mfma_f32_16x16x32_bf16 v[0:3], v[230:233], v[214:217], v[0:3]
	s_setprio 0
	s_barrier
	v_add_u32_e32 v154, 0x18000, v143
	ds_read_b128 v[138:141], v154
	ds_read_b128 v[146:149], v154 offset:1024
	ds_read_b128 v[150:153], v154 offset:2048
	ds_read_b128 v[154:157], v154 offset:3072
	v_add_u32_e32 v188, 0x1c000, v143
	ds_read_b128 v[218:221], v188
	ds_read_b128 v[222:225], v188 offset:1024
	ds_read_b128 v[226:229], v188 offset:2048
	ds_read_b128 v[230:233], v188 offset:3072
	s_add_u32 s2, s72, 0x80000
	s_addc_u32 s3, s73, 0
	s_mov_b32 m0, s74
	v_lshl_add_u64 v[204:205], s[2:3], 0, v[132:133]
	ds_read_b128 v[158:161], v145 offset:32768
	ds_read_b128 v[162:165], v145 offset:33792
	ds_read_b128 v[166:169], v145 offset:34816
	ds_read_b128 v[170:173], v145 offset:35840
	ds_read_b128 v[182:185], v145 offset:36864
	ds_read_b128 v[206:209], v145 offset:37888
	ds_read_b128 v[210:213], v145 offset:38912
	ds_read_b128 v[214:217], v145 offset:39936
	global_load_lds_dwordx4 v[204:205], off
	v_lshl_add_u64 v[204:205], s[2:3], 0, v[130:131]
	s_mov_b32 m0, s75
	s_nop 0
	global_load_lds_dwordx4 v[204:205], off
	s_waitcnt lgkmcnt(0)
	s_waitcnt vmcnt(8)
	s_barrier
	s_setprio 1
	v_mfma_f32_16x16x32_bf16 v[124:127], v[138:141], v[158:161], v[124:127]
	v_mfma_f32_16x16x32_bf16 v[120:123], v[150:153], v[158:161], v[120:123]
	v_mfma_f32_16x16x32_bf16 v[116:119], v[138:141], v[166:169], v[116:119]
	v_mfma_f32_16x16x32_bf16 v[108:111], v[150:153], v[166:169], v[108:111]
	v_mfma_f32_16x16x32_bf16 v[100:103], v[138:141], v[182:185], v[100:103]
	v_mfma_f32_16x16x32_bf16 v[92:95], v[150:153], v[182:185], v[92:95]
	v_mfma_f32_16x16x32_bf16 v[84:87], v[138:141], v[210:213], v[84:87]
	v_mfma_f32_16x16x32_bf16 v[76:79], v[150:153], v[210:213], v[76:79]
	v_mfma_f32_16x16x32_bf16 v[124:127], v[146:149], v[162:165], v[124:127]
	v_mfma_f32_16x16x32_bf16 v[120:123], v[154:157], v[162:165], v[120:123]
	v_mfma_f32_16x16x32_bf16 v[116:119], v[146:149], v[170:173], v[116:119]
	v_mfma_f32_16x16x32_bf16 v[108:111], v[154:157], v[170:173], v[108:111]
	v_mfma_f32_16x16x32_bf16 v[100:103], v[146:149], v[206:209], v[100:103]
	v_mfma_f32_16x16x32_bf16 v[92:95], v[154:157], v[206:209], v[92:95]
	v_mfma_f32_16x16x32_bf16 v[84:87], v[146:149], v[214:217], v[84:87]
	v_mfma_f32_16x16x32_bf16 v[76:79], v[154:157], v[214:217], v[76:79]
	v_mfma_f32_16x16x32_bf16 v[112:115], v[218:221], v[158:161], v[112:115]
	v_mfma_f32_16x16x32_bf16 v[104:107], v[226:229], v[158:161], v[104:107]
	v_mfma_f32_16x16x32_bf16 v[96:99], v[218:221], v[166:169], v[96:99]
	v_mfma_f32_16x16x32_bf16 v[88:91], v[226:229], v[166:169], v[88:91]
	v_mfma_f32_16x16x32_bf16 v[80:83], v[218:221], v[182:185], v[80:83]
	v_mfma_f32_16x16x32_bf16 v[72:75], v[226:229], v[182:185], v[72:75]
	v_mfma_f32_16x16x32_bf16 v[68:71], v[218:221], v[210:213], v[68:71]
	v_mfma_f32_16x16x32_bf16 v[64:67], v[226:229], v[210:213], v[64:67]
	v_mfma_f32_16x16x32_bf16 v[112:115], v[222:225], v[162:165], v[112:115]
	v_mfma_f32_16x16x32_bf16 v[104:107], v[230:233], v[162:165], v[104:107]
	v_mfma_f32_16x16x32_bf16 v[96:99], v[222:225], v[170:173], v[96:99]
	v_mfma_f32_16x16x32_bf16 v[88:91], v[230:233], v[170:173], v[88:91]
	v_mfma_f32_16x16x32_bf16 v[80:83], v[222:225], v[206:209], v[80:83]
	v_mfma_f32_16x16x32_bf16 v[72:75], v[230:233], v[206:209], v[72:75]
	v_mfma_f32_16x16x32_bf16 v[68:71], v[222:225], v[214:217], v[68:71]
	v_mfma_f32_16x16x32_bf16 v[64:67], v[230:233], v[214:217], v[64:67]
	s_setprio 0
	s_barrier
	ds_read_b128 v[158:161], v145 offset:49152
	ds_read_b128 v[162:165], v145 offset:50176
	ds_read_b128 v[166:169], v145 offset:51200
	ds_read_b128 v[170:173], v145 offset:52224
	ds_read_b128 v[182:185], v145 offset:53248
	ds_read_b128 v[206:209], v145 offset:54272
	ds_read_b128 v[210:213], v145 offset:55296
	ds_read_b128 v[214:217], v145 offset:56320
	v_lshl_add_u64 v[174:175], v[174:175], 0, s[20:21]
	s_add_i32 m0, s53, 0x18000
	s_nop 0
	global_load_lds_dwordx4 v[174:175], off
	v_lshl_add_u64 v[174:175], v[186:187], 0, s[20:21]
	s_add_i32 m0, s53, 0x1a000
	s_nop 0
	global_load_lds_dwordx4 v[174:175], off
	s_mov_b32 m0, s76
	v_lshl_add_u64 v[234:235], v[200:201], 0, s[20:21]
	global_load_lds_dwordx4 v[234:235], off
	v_lshl_add_u64 v[234:235], v[202:203], 0, s[20:21]
	s_mov_b32 m0, s77
	s_nop 0
	global_load_lds_dwordx4 v[234:235], off
	s_add_u32 s2, s70, 0x80080
	s_addc_u32 s3, s71, 0
	v_lshl_add_u64 v[236:237], s[2:3], 0, v[176:177]
	s_add_i32 m0, s53, 0x1c000
	s_nop 0
	global_load_lds_dwordx4 v[236:237], off
	v_lshl_add_u64 v[236:237], s[2:3], 0, v[128:129]
	s_add_i32 m0, s53, 0x1e000
	s_nop 0
	global_load_lds_dwordx4 v[236:237], off
	s_waitcnt lgkmcnt(0)
	s_waitcnt vmcnt(8)
	s_barrier
	s_setprio 1
	v_mfma_f32_16x16x32_bf16 v[60:63], v[138:141], v[158:161], v[60:63]
	v_mfma_f32_16x16x32_bf16 v[56:59], v[150:153], v[158:161], v[56:59]
	v_mfma_f32_16x16x32_bf16 v[52:55], v[138:141], v[166:169], v[52:55]
	v_mfma_f32_16x16x32_bf16 v[44:47], v[150:153], v[166:169], v[44:47]
	v_mfma_f32_16x16x32_bf16 v[36:39], v[138:141], v[182:185], v[36:39]
	v_mfma_f32_16x16x32_bf16 v[28:31], v[150:153], v[182:185], v[28:31]
	v_mfma_f32_16x16x32_bf16 v[20:23], v[138:141], v[210:213], v[20:23]
	v_mfma_f32_16x16x32_bf16 v[12:15], v[150:153], v[210:213], v[12:15]
	v_mfma_f32_16x16x32_bf16 v[60:63], v[146:149], v[162:165], v[60:63]
	v_mfma_f32_16x16x32_bf16 v[56:59], v[154:157], v[162:165], v[56:59]
	v_mfma_f32_16x16x32_bf16 v[52:55], v[146:149], v[170:173], v[52:55]
	v_mfma_f32_16x16x32_bf16 v[44:47], v[154:157], v[170:173], v[44:47]
	v_mfma_f32_16x16x32_bf16 v[36:39], v[146:149], v[206:209], v[36:39]
	v_mfma_f32_16x16x32_bf16 v[28:31], v[154:157], v[206:209], v[28:31]
	v_mfma_f32_16x16x32_bf16 v[20:23], v[146:149], v[214:217], v[20:23]
	v_mfma_f32_16x16x32_bf16 v[12:15], v[154:157], v[214:217], v[12:15]
	v_mfma_f32_16x16x32_bf16 v[48:51], v[218:221], v[158:161], v[48:51]
	v_mfma_f32_16x16x32_bf16 v[40:43], v[226:229], v[158:161], v[40:43]
	v_mfma_f32_16x16x32_bf16 v[32:35], v[218:221], v[166:169], v[32:35]
	v_mfma_f32_16x16x32_bf16 v[24:27], v[226:229], v[166:169], v[24:27]
	v_mfma_f32_16x16x32_bf16 v[16:19], v[218:221], v[182:185], v[16:19]
	v_mfma_f32_16x16x32_bf16 v[8:11], v[226:229], v[182:185], v[8:11]
	v_mfma_f32_16x16x32_bf16 v[4:7], v[218:221], v[210:213], v[4:7]
	v_mfma_f32_16x16x32_bf16 v[0:3], v[226:229], v[210:213], v[0:3]
	v_mfma_f32_16x16x32_bf16 v[48:51], v[222:225], v[162:165], v[48:51]
	v_mfma_f32_16x16x32_bf16 v[40:43], v[230:233], v[162:165], v[40:43]
	v_mfma_f32_16x16x32_bf16 v[32:35], v[222:225], v[170:173], v[32:35]
	v_mfma_f32_16x16x32_bf16 v[24:27], v[230:233], v[170:173], v[24:27]
	v_mfma_f32_16x16x32_bf16 v[16:19], v[222:225], v[206:209], v[16:19]
	v_mfma_f32_16x16x32_bf16 v[8:11], v[230:233], v[206:209], v[8:11]
	v_mfma_f32_16x16x32_bf16 v[4:7], v[222:225], v[214:217], v[4:7]
	v_mfma_f32_16x16x32_bf16 v[0:3], v[230:233], v[214:217], v[0:3]
	s_setprio 0
	s_add_i32 s87, s87, 2
	s_add_u32 s68, s68, 0x100
	s_addc_u32 s69, s69, 0
	s_add_u32 s83, s83, 0x100
	s_addc_u32 s86, s86, 0
	s_cmp_gt_u32 s87, 29
	s_barrier
	s_cbranch_scc0 .LBB0_189
	v_readlane_b32 s2, v253, 5
	v_lshl_or_b32 v140, s79, 8, v144
	v_readlane_b32 s3, v253, 6
	v_lshl_add_u32 v148, s80, 8, v142
	v_ashrrev_i32_e32 v141, 31, v140
	v_mov_b64_e32 v[138:139], s[2:3]
	v_mad_i64_i32 v[146:147], s[2:3], v148, s84, v[138:139]
	v_lshlrev_b64 v[140:141], 1, v[140:141]
	v_lshl_add_u64 v[146:147], v[146:147], 0, v[140:141]
	v_cvt_pk_bf16_f32 v124, v124, v125
	v_cvt_pk_bf16_f32 v125, v126, v127
	v_cvt_pk_bf16_f32 v126, v120, v121
	v_cvt_pk_bf16_f32 v127, v122, v123
	global_store_dwordx4 v[146:147], v[124:127], off
	v_cvt_pk_bf16_f32 v112, v112, v113
	v_cvt_pk_bf16_f32 v113, v114, v115
	v_cvt_pk_bf16_f32 v114, v104, v105
	v_or_b32_e32 v104, 16, v148
	v_mad_i64_i32 v[104:105], s[2:3], v104, s84, v[138:139]
	v_cvt_pk_bf16_f32 v115, v106, v107
	global_store_dwordx4 v[146:147], v[112:115], off offset:256
	s_and_b64 vcc, exec, s[38:39]
	s_mov_b32 s79, s40
	v_lshl_add_u64 v[112:113], v[104:105], 0, v[140:141]
	v_cvt_pk_bf16_f32 v104, v116, v117
	v_cvt_pk_bf16_f32 v105, v118, v119
	v_cvt_pk_bf16_f32 v106, v108, v109
	v_cvt_pk_bf16_f32 v107, v110, v111
	global_store_dwordx4 v[112:113], v[104:107], off
	v_cvt_pk_bf16_f32 v96, v96, v97
	v_cvt_pk_bf16_f32 v97, v98, v99
	v_cvt_pk_bf16_f32 v98, v88, v89
	v_or_b32_e32 v88, 32, v148
	v_mad_i64_i32 v[88:89], s[2:3], v88, s84, v[138:139]
	v_cvt_pk_bf16_f32 v99, v90, v91
	global_store_dwordx4 v[112:113], v[96:99], off offset:256
	s_mov_b32 s80, s42
	s_mov_b64 s[70:71], s[46:47]
	v_lshl_add_u64 v[96:97], v[88:89], 0, v[140:141]
	v_cvt_pk_bf16_f32 v88, v100, v101
	v_cvt_pk_bf16_f32 v89, v102, v103
	v_cvt_pk_bf16_f32 v90, v92, v93
	v_cvt_pk_bf16_f32 v91, v94, v95
	global_store_dwordx4 v[96:97], v[88:91], off
	v_cvt_pk_bf16_f32 v80, v80, v81
	v_cvt_pk_bf16_f32 v81, v82, v83
	v_cvt_pk_bf16_f32 v82, v72, v73
	v_or_b32_e32 v72, 48, v148
	v_mad_i64_i32 v[72:73], s[2:3], v72, s84, v[138:139]
	v_cvt_pk_bf16_f32 v83, v74, v75
	global_store_dwordx4 v[96:97], v[80:83], off offset:256
	s_mov_b64 s[68:69], s[44:45]
	s_nop 0
	v_lshl_add_u64 v[80:81], v[72:73], 0, v[140:141]
	v_cvt_pk_bf16_f32 v72, v84, v85
	v_cvt_pk_bf16_f32 v73, v86, v87
	v_cvt_pk_bf16_f32 v74, v76, v77
	v_cvt_pk_bf16_f32 v75, v78, v79
	global_store_dwordx4 v[80:81], v[72:75], off
	v_cvt_pk_bf16_f32 v68, v68, v69
	v_cvt_pk_bf16_f32 v69, v70, v71
	v_cvt_pk_bf16_f32 v70, v64, v65
	v_add_u32_e32 v64, 0x80, v148
	v_mad_i64_i32 v[64:65], s[2:3], v64, s84, v[138:139]
	v_lshl_add_u64 v[64:65], v[64:65], 0, v[140:141]
	v_cvt_pk_bf16_f32 v71, v66, v67
	global_store_dwordx4 v[80:81], v[68:71], off offset:256
	v_cvt_pk_bf16_f32 v60, v60, v61
	v_cvt_pk_bf16_f32 v61, v62, v63
	v_cvt_pk_bf16_f32 v62, v56, v57
	v_cvt_pk_bf16_f32 v63, v58, v59
	global_store_dwordx4 v[64:65], v[60:63], off
	v_cvt_pk_bf16_f32 v48, v48, v49
	v_cvt_pk_bf16_f32 v49, v50, v51
	v_cvt_pk_bf16_f32 v50, v40, v41
	v_add_u32_e32 v40, 0x90, v148
	v_mad_i64_i32 v[40:41], s[2:3], v40, s84, v[138:139]
	v_cvt_pk_bf16_f32 v51, v42, v43
	global_store_dwordx4 v[64:65], v[48:51], off offset:256
	s_nop 1
	v_lshl_add_u64 v[48:49], v[40:41], 0, v[140:141]
	v_cvt_pk_bf16_f32 v40, v52, v53
	v_cvt_pk_bf16_f32 v41, v54, v55
	v_cvt_pk_bf16_f32 v42, v44, v45
	v_cvt_pk_bf16_f32 v43, v46, v47
	global_store_dwordx4 v[48:49], v[40:43], off
	v_cvt_pk_bf16_f32 v32, v32, v33
	v_cvt_pk_bf16_f32 v33, v34, v35
	v_cvt_pk_bf16_f32 v34, v24, v25
	v_add_u32_e32 v24, 0xa0, v148
	v_mad_i64_i32 v[24:25], s[2:3], v24, s84, v[138:139]
	v_cvt_pk_bf16_f32 v35, v26, v27
	global_store_dwordx4 v[48:49], v[32:35], off offset:256
	s_nop 1
	v_lshl_add_u64 v[32:33], v[24:25], 0, v[140:141]
	v_cvt_pk_bf16_f32 v24, v36, v37
	v_cvt_pk_bf16_f32 v25, v38, v39
	v_cvt_pk_bf16_f32 v26, v28, v29
	v_cvt_pk_bf16_f32 v27, v30, v31
	global_store_dwordx4 v[32:33], v[24:27], off
	v_cvt_pk_bf16_f32 v16, v16, v17
	v_cvt_pk_bf16_f32 v17, v18, v19
	v_cvt_pk_bf16_f32 v18, v8, v9
	v_add_u32_e32 v8, 0xb0, v148
	v_mad_i64_i32 v[8:9], s[2:3], v8, s84, v[138:139]
	v_cvt_pk_bf16_f32 v19, v10, v11
	global_store_dwordx4 v[32:33], v[16:19], off offset:256
	s_nop 1
	v_lshl_add_u64 v[16:17], v[8:9], 0, v[140:141]
	v_cvt_pk_bf16_f32 v8, v20, v21
	v_cvt_pk_bf16_f32 v9, v22, v23
	v_cvt_pk_bf16_f32 v10, v12, v13
	v_cvt_pk_bf16_f32 v11, v14, v15
	global_store_dwordx4 v[16:17], v[8:11], off
	v_cvt_pk_bf16_f32 v4, v4, v5
	v_cvt_pk_bf16_f32 v5, v6, v7
	v_cvt_pk_bf16_f32 v6, v0, v1
	v_cvt_pk_bf16_f32 v7, v2, v3
	global_store_dwordx4 v[16:17], v[4:7], off offset:256
	s_cbranch_vccz .LBB0_186
	s_waitcnt vmcnt(0)
	s_cmpk_gt_u32 s34, 0xff
	s_cbranch_scc1 .LBB0_193
	s_barrier
